# grid barrier: follower invalidate at arrival; XCD leader invalidate issued behind the cross-XCD arrival atomic (counted vmcnt(1)); top-level last arriver releases every XCD directly
# speedup vs baseline: 1.0100x; 1.0047x over previous
; __device__ __forceinline__ unsigned xb_ld(unsigned* p)              { return __hip_atomic_load(p, __ATOMIC_RELAXED, __HIP_MEMORY_SCOPE_AGENT); }
; __device__ __forceinline__ unsigned xb_add(unsigned* p, unsigned v) { return __hip_atomic_fetch_add(p, v, __ATOMIC_RELAXED, __HIP_MEMORY_SCOPE_AGENT); }
; #define XB_SPIN(cond, bar) do { unsigned _sp = 0; while (cond) { __builtin_amdgcn_s_sleep(1); \
;     if ((++_sp & 255u) == 0u) { if (xb_ld(&(bar)[XB_TMO])) break; if (_sp > XB_SPIN_CAP) { atomicAdd(&(bar)[XB_TMO], 1u); break; } } } } while (0)
; __device__ __forceinline__ void xcd_barrier(unsigned* bar, volatile LAS unsigned* st, bool tid0) {
;     ...
;             const unsigned og = xb_add(&bar[XB_TOP], 1u);
;             const unsigned tg = og / nx;
;             if (og + 1u == (tg + 1u) * nx) xb_add(&bar[XB_TOPGEN], 1u);
;             else XB_SPIN(xb_ld(&bar[XB_TOPGEN]) == tg, bar);
;             __builtin_amdgcn_fence(__ATOMIC_ACQUIRE, "agent");
.LBB0_64:
	s_or_b64 exec, exec, s[8:9]
	buffer_inv sc1
	v_cvt_f32_u32_e32 v4, v1
	s_waitcnt vmcnt(1)
	v_readfirstlane_b32 s2, v3
	s_add_u32 s8, s52, 0x3500
	s_addc_u32 s9, s53, 0
	v_rcp_iflag_f32_e32 v4, v4
	v_add_u32_e32 v2, s2, v2
	v_add_u32_e32 v5, 1, v2
	s_mov_b64 s[10:11], -1
	v_mul_f32_e32 v3, 0x4f7ffffe, v4
	v_cvt_u32_f32_e32 v3, v3
	v_sub_u32_e32 v4, 0, v1
	v_mul_lo_u32 v4, v4, v3
	v_mul_hi_u32 v4, v3, v4
	v_add_u32_e32 v3, v3, v4
	v_mul_hi_u32 v3, v2, v3
	v_mul_lo_u32 v4, v3, v1
	v_sub_u32_e32 v2, v2, v4
	v_add_u32_e32 v6, 1, v3
	v_cmp_ge_u32_e32 vcc, v2, v1
	v_sub_u32_e32 v4, v2, v1
	s_nop 0
	v_cndmask_b32_e32 v3, v3, v6, vcc
	v_cndmask_b32_e32 v2, v2, v4, vcc
	v_add_u32_e32 v4, 1, v3
	v_cmp_ge_u32_e32 vcc, v2, v1
	s_nop 1
	v_cndmask_b32_e32 v4, v3, v4, vcc
	v_mul_lo_u32 v2, v1, v4
	v_add_u32_e32 v1, v2, v1
	v_cmp_ne_u32_e32 vcc, v5, v1
	v_mov_b64_e32 v[2:3], s[8:9]
	s_cbranch_vccnz .Lxb_bcast_skip_0
	v_mov_b32_e32 v5, 0x2400
	v_mov_b32_e32 v6, 1
	global_atomic_add v5, v6, s[52:53]
	global_atomic_add v5, v6, s[52:53] offset:256
	global_atomic_add v5, v6, s[52:53] offset:512
	global_atomic_add v5, v6, s[52:53] offset:768
	global_atomic_add v5, v6, s[52:53] offset:1024
	global_atomic_add v5, v6, s[52:53] offset:1280
	global_atomic_add v5, v6, s[52:53] offset:1536
	global_atomic_add v5, v6, s[52:53] offset:1792
	global_atomic_add v5, v6, s[52:53] offset:2048
	global_atomic_add v5, v6, s[52:53] offset:2304
	global_atomic_add v5, v6, s[52:53] offset:2560
	global_atomic_add v5, v6, s[52:53] offset:2816
	global_atomic_add v5, v6, s[52:53] offset:3072
	global_atomic_add v5, v6, s[52:53] offset:3328
	global_atomic_add v5, v6, s[52:53] offset:3584
	global_atomic_add v5, v6, s[52:53] offset:3840

; __device__ __forceinline__ unsigned xb_ld(unsigned* p)              { return __hip_atomic_load(p, __ATOMIC_RELAXED, __HIP_MEMORY_SCOPE_AGENT); }
; __device__ __forceinline__ unsigned xb_add(unsigned* p, unsigned v) { return __hip_atomic_fetch_add(p, v, __ATOMIC_RELAXED, __HIP_MEMORY_SCOPE_AGENT); }
; #define XB_SPIN(cond, bar) do { unsigned _sp = 0; while (cond) { __builtin_amdgcn_s_sleep(1); \
;     if ((++_sp & 255u) == 0u) { if (xb_ld(&(bar)[XB_TMO])) break; if (_sp > XB_SPIN_CAP) { atomicAdd(&(bar)[XB_TMO], 1u); break; } } } } while (0)
; __device__ __forceinline__ void xcd_barrier(unsigned* bar, volatile LAS unsigned* st, bool tid0) {
;     ...
;             const unsigned og = xb_add(&bar[XB_TOP], 1u);
;             const unsigned tg = og / nx;
;             if (og + 1u == (tg + 1u) * nx) xb_add(&bar[XB_TOPGEN], 1u);
;             else XB_SPIN(xb_ld(&bar[XB_TOPGEN]) == tg, bar);
;             __builtin_amdgcn_fence(__ATOMIC_ACQUIRE, "agent");
.LBB0_206:
	s_or_b64 exec, exec, s[10:11]
	buffer_inv sc1
	v_cvt_f32_u32_e32 v3, v0
	s_waitcnt vmcnt(1)
	v_readfirstlane_b32 s2, v2
	s_add_u32 s10, s52, 0x3500
	s_addc_u32 s11, s53, 0
	v_rcp_iflag_f32_e32 v3, v3
	v_add_u32_e32 v1, s2, v1
	v_add_u32_e32 v4, 1, v1
	s_mov_b64 s[12:13], -1
	v_mul_f32_e32 v2, 0x4f7ffffe, v3
	v_cvt_u32_f32_e32 v2, v2
	v_sub_u32_e32 v3, 0, v0
	v_mul_lo_u32 v3, v3, v2
	v_mul_hi_u32 v3, v2, v3
	v_add_u32_e32 v2, v2, v3
	v_mul_hi_u32 v2, v1, v2
	v_mul_lo_u32 v3, v2, v0
	v_sub_u32_e32 v1, v1, v3
	v_add_u32_e32 v5, 1, v2
	v_cmp_ge_u32_e32 vcc, v1, v0
	v_sub_u32_e32 v3, v1, v0
	s_nop 0
	v_cndmask_b32_e32 v2, v2, v5, vcc
	v_cndmask_b32_e32 v1, v1, v3, vcc
	v_add_u32_e32 v3, 1, v2
	v_cmp_ge_u32_e32 vcc, v1, v0
	s_nop 1
	v_cndmask_b32_e32 v2, v2, v3, vcc
	v_mul_lo_u32 v1, v0, v2
	v_add_u32_e32 v0, v1, v0
	v_cmp_ne_u32_e32 vcc, v4, v0
	v_mov_b64_e32 v[0:1], s[10:11]
	s_cbranch_vccnz .Lxb_bcast_skip_1
	v_mov_b32_e32 v3, 0x2400
	v_mov_b32_e32 v4, 1
	global_atomic_add v3, v4, s[52:53]
	global_atomic_add v3, v4, s[52:53] offset:256
	global_atomic_add v3, v4, s[52:53] offset:512
	global_atomic_add v3, v4, s[52:53] offset:768
	global_atomic_add v3, v4, s[52:53] offset:1024
	global_atomic_add v3, v4, s[52:53] offset:1280
	global_atomic_add v3, v4, s[52:53] offset:1536
	global_atomic_add v3, v4, s[52:53] offset:1792
	global_atomic_add v3, v4, s[52:53] offset:2048
	global_atomic_add v3, v4, s[52:53] offset:2304
	global_atomic_add v3, v4, s[52:53] offset:2560
	global_atomic_add v3, v4, s[52:53] offset:2816
	global_atomic_add v3, v4, s[52:53] offset:3072
	global_atomic_add v3, v4, s[52:53] offset:3328
	global_atomic_add v3, v4, s[52:53] offset:3584
	global_atomic_add v3, v4, s[52:53] offset:3840

; __device__ __forceinline__ unsigned xb_ld(unsigned* p)              { return __hip_atomic_load(p, __ATOMIC_RELAXED, __HIP_MEMORY_SCOPE_AGENT); }
; __device__ __forceinline__ unsigned xb_add(unsigned* p, unsigned v) { return __hip_atomic_fetch_add(p, v, __ATOMIC_RELAXED, __HIP_MEMORY_SCOPE_AGENT); }
; #define XB_SPIN(cond, bar) do { unsigned _sp = 0; while (cond) { __builtin_amdgcn_s_sleep(1); \
;     if ((++_sp & 255u) == 0u) { if (xb_ld(&(bar)[XB_TMO])) break; if (_sp > XB_SPIN_CAP) { atomicAdd(&(bar)[XB_TMO], 1u); break; } } } } while (0)
; __device__ __forceinline__ void xcd_barrier(unsigned* bar, volatile LAS unsigned* st, bool tid0) {
;     ...
;             const unsigned og = xb_add(&bar[XB_TOP], 1u);
;             const unsigned tg = og / nx;
;             if (og + 1u == (tg + 1u) * nx) xb_add(&bar[XB_TOPGEN], 1u);
;             else XB_SPIN(xb_ld(&bar[XB_TOPGEN]) == tg, bar);
;             __builtin_amdgcn_fence(__ATOMIC_ACQUIRE, "agent");
.LBB0_270:
	s_or_b64 exec, exec, s[10:11]
	buffer_inv sc1
	v_cvt_f32_u32_e32 v3, v0
	s_waitcnt vmcnt(1)
	v_readfirstlane_b32 s3, v2
	s_add_u32 s10, s52, 0x3500
	s_addc_u32 s11, s53, 0
	v_rcp_iflag_f32_e32 v3, v3
	v_add_u32_e32 v1, s3, v1
	v_add_u32_e32 v4, 1, v1
	s_mov_b64 s[16:17], -1
	v_mul_f32_e32 v2, 0x4f7ffffe, v3
	v_cvt_u32_f32_e32 v2, v2
	v_sub_u32_e32 v3, 0, v0
	v_mul_lo_u32 v3, v3, v2
	v_mul_hi_u32 v3, v2, v3
	v_add_u32_e32 v2, v2, v3
	v_mul_hi_u32 v2, v1, v2
	v_mul_lo_u32 v3, v2, v0
	v_sub_u32_e32 v1, v1, v3
	v_add_u32_e32 v5, 1, v2
	v_cmp_ge_u32_e32 vcc, v1, v0
	v_sub_u32_e32 v3, v1, v0
	s_nop 0
	v_cndmask_b32_e32 v2, v2, v5, vcc
	v_cndmask_b32_e32 v1, v1, v3, vcc
	v_add_u32_e32 v3, 1, v2
	v_cmp_ge_u32_e32 vcc, v1, v0
	s_nop 1
	v_cndmask_b32_e32 v2, v2, v3, vcc
	v_mul_lo_u32 v1, v0, v2
	v_add_u32_e32 v0, v1, v0
	v_cmp_ne_u32_e32 vcc, v4, v0
	v_mov_b64_e32 v[0:1], s[10:11]
	s_cbranch_vccnz .Lxb_bcast_skip_2
	v_mov_b32_e32 v3, 0x2400
	v_mov_b32_e32 v4, 1
	global_atomic_add v3, v4, s[52:53]
	global_atomic_add v3, v4, s[52:53] offset:256
	global_atomic_add v3, v4, s[52:53] offset:512
	global_atomic_add v3, v4, s[52:53] offset:768
	global_atomic_add v3, v4, s[52:53] offset:1024
	global_atomic_add v3, v4, s[52:53] offset:1280
	global_atomic_add v3, v4, s[52:53] offset:1536
	global_atomic_add v3, v4, s[52:53] offset:1792
	global_atomic_add v3, v4, s[52:53] offset:2048
	global_atomic_add v3, v4, s[52:53] offset:2304
	global_atomic_add v3, v4, s[52:53] offset:2560
	global_atomic_add v3, v4, s[52:53] offset:2816
	global_atomic_add v3, v4, s[52:53] offset:3072
	global_atomic_add v3, v4, s[52:53] offset:3328
	global_atomic_add v3, v4, s[52:53] offset:3584
	global_atomic_add v3, v4, s[52:53] offset:3840

; __device__ __forceinline__ unsigned xb_ld(unsigned* p)              { return __hip_atomic_load(p, __ATOMIC_RELAXED, __HIP_MEMORY_SCOPE_AGENT); }
; __device__ __forceinline__ unsigned xb_add(unsigned* p, unsigned v) { return __hip_atomic_fetch_add(p, v, __ATOMIC_RELAXED, __HIP_MEMORY_SCOPE_AGENT); }
; #define XB_SPIN(cond, bar) do { unsigned _sp = 0; while (cond) { __builtin_amdgcn_s_sleep(1); \
;     if ((++_sp & 255u) == 0u) { if (xb_ld(&(bar)[XB_TMO])) break; if (_sp > XB_SPIN_CAP) { atomicAdd(&(bar)[XB_TMO], 1u); break; } } } } while (0)
; __device__ __forceinline__ void xcd_barrier(unsigned* bar, volatile LAS unsigned* st, bool tid0) {
;     ...
;             const unsigned og = xb_add(&bar[XB_TOP], 1u);
;             const unsigned tg = og / nx;
;             if (og + 1u == (tg + 1u) * nx) xb_add(&bar[XB_TOPGEN], 1u);
;             else XB_SPIN(xb_ld(&bar[XB_TOPGEN]) == tg, bar);
;             __builtin_amdgcn_fence(__ATOMIC_ACQUIRE, "agent");
.LBB0_328:
	s_or_b64 exec, exec, s[8:9]
	buffer_inv sc1
	v_cvt_f32_u32_e32 v3, v0
	s_waitcnt vmcnt(1)
	v_readfirstlane_b32 s3, v2
	s_add_u32 s8, s52, 0x3500
	s_addc_u32 s9, s53, 0
	v_rcp_iflag_f32_e32 v3, v3
	v_add_u32_e32 v1, s3, v1
	v_add_u32_e32 v4, 1, v1
	s_mov_b64 s[10:11], -1
	v_mul_f32_e32 v2, 0x4f7ffffe, v3
	v_cvt_u32_f32_e32 v2, v2
	v_sub_u32_e32 v3, 0, v0
	v_mul_lo_u32 v3, v3, v2
	v_mul_hi_u32 v3, v2, v3
	v_add_u32_e32 v2, v2, v3
	v_mul_hi_u32 v2, v1, v2
	v_mul_lo_u32 v3, v2, v0
	v_sub_u32_e32 v1, v1, v3
	v_add_u32_e32 v5, 1, v2
	v_cmp_ge_u32_e32 vcc, v1, v0
	v_sub_u32_e32 v3, v1, v0
	s_nop 0
	v_cndmask_b32_e32 v2, v2, v5, vcc
	v_cndmask_b32_e32 v1, v1, v3, vcc
	v_add_u32_e32 v3, 1, v2
	v_cmp_ge_u32_e32 vcc, v1, v0
	s_nop 1
	v_cndmask_b32_e32 v2, v2, v3, vcc
	v_mul_lo_u32 v1, v0, v2
	v_add_u32_e32 v0, v1, v0
	v_cmp_ne_u32_e32 vcc, v4, v0
	v_mov_b64_e32 v[0:1], s[8:9]
	s_cbranch_vccnz .Lxb_bcast_skip_3
	v_mov_b32_e32 v3, 0x2400
	v_mov_b32_e32 v4, 1
	global_atomic_add v3, v4, s[52:53]
	global_atomic_add v3, v4, s[52:53] offset:256
	global_atomic_add v3, v4, s[52:53] offset:512
	global_atomic_add v3, v4, s[52:53] offset:768
	global_atomic_add v3, v4, s[52:53] offset:1024
	global_atomic_add v3, v4, s[52:53] offset:1280
	global_atomic_add v3, v4, s[52:53] offset:1536
	global_atomic_add v3, v4, s[52:53] offset:1792
	global_atomic_add v3, v4, s[52:53] offset:2048
	global_atomic_add v3, v4, s[52:53] offset:2304
	global_atomic_add v3, v4, s[52:53] offset:2560
	global_atomic_add v3, v4, s[52:53] offset:2816
	global_atomic_add v3, v4, s[52:53] offset:3072
	global_atomic_add v3, v4, s[52:53] offset:3328
	global_atomic_add v3, v4, s[52:53] offset:3584
	global_atomic_add v3, v4, s[52:53] offset:3840

; __device__ __forceinline__ unsigned xb_ld(unsigned* p)              { return __hip_atomic_load(p, __ATOMIC_RELAXED, __HIP_MEMORY_SCOPE_AGENT); }
; __device__ __forceinline__ unsigned xb_add(unsigned* p, unsigned v) { return __hip_atomic_fetch_add(p, v, __ATOMIC_RELAXED, __HIP_MEMORY_SCOPE_AGENT); }
; #define XB_SPIN(cond, bar) do { unsigned _sp = 0; while (cond) { __builtin_amdgcn_s_sleep(1); \
;     if ((++_sp & 255u) == 0u) { if (xb_ld(&(bar)[XB_TMO])) break; if (_sp > XB_SPIN_CAP) { atomicAdd(&(bar)[XB_TMO], 1u); break; } } } } while (0)
; __device__ __forceinline__ void xcd_barrier(unsigned* bar, volatile LAS unsigned* st, bool tid0) {
;     ...
;             const unsigned og = xb_add(&bar[XB_TOP], 1u);
;             const unsigned tg = og / nx;
;             if (og + 1u == (tg + 1u) * nx) xb_add(&bar[XB_TOPGEN], 1u);
;             else XB_SPIN(xb_ld(&bar[XB_TOPGEN]) == tg, bar);
;             __builtin_amdgcn_fence(__ATOMIC_ACQUIRE, "agent");
.LBB0_479:
	s_or_b64 exec, exec, s[8:9]
	buffer_inv sc1
	v_cvt_f32_u32_e32 v3, v0
	s_waitcnt vmcnt(1)
	v_readfirstlane_b32 s2, v2
	s_add_u32 s8, s52, 0x3500
	s_addc_u32 s9, s53, 0
	v_rcp_iflag_f32_e32 v3, v3
	v_add_u32_e32 v1, s2, v1
	v_add_u32_e32 v4, 1, v1
	s_mov_b64 s[10:11], -1
	v_mul_f32_e32 v2, 0x4f7ffffe, v3
	v_cvt_u32_f32_e32 v2, v2
	v_sub_u32_e32 v3, 0, v0
	v_mul_lo_u32 v3, v3, v2
	v_mul_hi_u32 v3, v2, v3
	v_add_u32_e32 v2, v2, v3
	v_mul_hi_u32 v2, v1, v2
	v_mul_lo_u32 v3, v2, v0
	v_sub_u32_e32 v1, v1, v3
	v_add_u32_e32 v5, 1, v2
	v_cmp_ge_u32_e32 vcc, v1, v0
	v_sub_u32_e32 v3, v1, v0
	s_nop 0
	v_cndmask_b32_e32 v2, v2, v5, vcc
	v_cndmask_b32_e32 v1, v1, v3, vcc
	v_add_u32_e32 v3, 1, v2
	v_cmp_ge_u32_e32 vcc, v1, v0
	s_nop 1
	v_cndmask_b32_e32 v2, v2, v3, vcc
	v_mul_lo_u32 v1, v0, v2
	v_add_u32_e32 v0, v1, v0
	v_cmp_ne_u32_e32 vcc, v4, v0
	v_mov_b64_e32 v[0:1], s[8:9]
	s_cbranch_vccnz .Lxb_bcast_skip_4
	v_mov_b32_e32 v3, 0x2400
	v_mov_b32_e32 v4, 1
	global_atomic_add v3, v4, s[52:53]
	global_atomic_add v3, v4, s[52:53] offset:256
	global_atomic_add v3, v4, s[52:53] offset:512
	global_atomic_add v3, v4, s[52:53] offset:768
	global_atomic_add v3, v4, s[52:53] offset:1024
	global_atomic_add v3, v4, s[52:53] offset:1280
	global_atomic_add v3, v4, s[52:53] offset:1536
	global_atomic_add v3, v4, s[52:53] offset:1792
	global_atomic_add v3, v4, s[52:53] offset:2048
	global_atomic_add v3, v4, s[52:53] offset:2304
	global_atomic_add v3, v4, s[52:53] offset:2560
	global_atomic_add v3, v4, s[52:53] offset:2816
	global_atomic_add v3, v4, s[52:53] offset:3072
	global_atomic_add v3, v4, s[52:53] offset:3328
	global_atomic_add v3, v4, s[52:53] offset:3584
	global_atomic_add v3, v4, s[52:53] offset:3840

; __device__ __forceinline__ unsigned xb_ld(unsigned* p)              { return __hip_atomic_load(p, __ATOMIC_RELAXED, __HIP_MEMORY_SCOPE_AGENT); }
; __device__ __forceinline__ unsigned xb_add(unsigned* p, unsigned v) { return __hip_atomic_fetch_add(p, v, __ATOMIC_RELAXED, __HIP_MEMORY_SCOPE_AGENT); }
; #define XB_SPIN(cond, bar) do { unsigned _sp = 0; while (cond) { __builtin_amdgcn_s_sleep(1); \
;     if ((++_sp & 255u) == 0u) { if (xb_ld(&(bar)[XB_TMO])) break; if (_sp > XB_SPIN_CAP) { atomicAdd(&(bar)[XB_TMO], 1u); break; } } } } while (0)
; __device__ __forceinline__ void xcd_barrier(unsigned* bar, volatile LAS unsigned* st, bool tid0) {
;     ...
;             const unsigned og = xb_add(&bar[XB_TOP], 1u);
;             const unsigned tg = og / nx;
;             if (og + 1u == (tg + 1u) * nx) xb_add(&bar[XB_TOPGEN], 1u);
;             else XB_SPIN(xb_ld(&bar[XB_TOPGEN]) == tg, bar);
;             __builtin_amdgcn_fence(__ATOMIC_ACQUIRE, "agent");
.LBB0_587:
	s_or_b64 exec, exec, s[14:15]
	buffer_inv sc1
	v_cvt_f32_u32_e32 v3, v0
	s_waitcnt vmcnt(1)
	v_readfirstlane_b32 s2, v2
	s_add_u32 s14, s52, 0x3500
	s_addc_u32 s15, s53, 0
	v_rcp_iflag_f32_e32 v3, v3
	v_add_u32_e32 v1, s2, v1
	v_add_u32_e32 v4, 1, v1
	s_mov_b64 s[16:17], -1
	v_mul_f32_e32 v2, 0x4f7ffffe, v3
	v_cvt_u32_f32_e32 v2, v2
	v_sub_u32_e32 v3, 0, v0
	v_mul_lo_u32 v3, v3, v2
	v_mul_hi_u32 v3, v2, v3
	v_add_u32_e32 v2, v2, v3
	v_mul_hi_u32 v2, v1, v2
	v_mul_lo_u32 v3, v2, v0
	v_sub_u32_e32 v1, v1, v3
	v_add_u32_e32 v5, 1, v2
	v_cmp_ge_u32_e32 vcc, v1, v0
	v_sub_u32_e32 v3, v1, v0
	s_nop 0
	v_cndmask_b32_e32 v2, v2, v5, vcc
	v_cndmask_b32_e32 v1, v1, v3, vcc
	v_add_u32_e32 v3, 1, v2
	v_cmp_ge_u32_e32 vcc, v1, v0
	s_nop 1
	v_cndmask_b32_e32 v2, v2, v3, vcc
	v_mul_lo_u32 v1, v0, v2
	v_add_u32_e32 v0, v1, v0
	v_cmp_ne_u32_e32 vcc, v4, v0
	v_mov_b64_e32 v[0:1], s[14:15]
	s_cbranch_vccnz .Lxb_bcast_skip_5
	v_mov_b32_e32 v3, 0x2400
	v_mov_b32_e32 v4, 1
	global_atomic_add v3, v4, s[52:53]
	global_atomic_add v3, v4, s[52:53] offset:256
	global_atomic_add v3, v4, s[52:53] offset:512
	global_atomic_add v3, v4, s[52:53] offset:768
	global_atomic_add v3, v4, s[52:53] offset:1024
	global_atomic_add v3, v4, s[52:53] offset:1280
	global_atomic_add v3, v4, s[52:53] offset:1536
	global_atomic_add v3, v4, s[52:53] offset:1792
	global_atomic_add v3, v4, s[52:53] offset:2048
	global_atomic_add v3, v4, s[52:53] offset:2304
	global_atomic_add v3, v4, s[52:53] offset:2560
	global_atomic_add v3, v4, s[52:53] offset:2816
	global_atomic_add v3, v4, s[52:53] offset:3072
	global_atomic_add v3, v4, s[52:53] offset:3328
	global_atomic_add v3, v4, s[52:53] offset:3584
	global_atomic_add v3, v4, s[52:53] offset:3840

; __device__ __forceinline__ unsigned xb_ld(unsigned* p)              { return __hip_atomic_load(p, __ATOMIC_RELAXED, __HIP_MEMORY_SCOPE_AGENT); }
; __device__ __forceinline__ unsigned xb_add(unsigned* p, unsigned v) { return __hip_atomic_fetch_add(p, v, __ATOMIC_RELAXED, __HIP_MEMORY_SCOPE_AGENT); }
; #define XB_SPIN(cond, bar) do { unsigned _sp = 0; while (cond) { __builtin_amdgcn_s_sleep(1); \
;     if ((++_sp & 255u) == 0u) { if (xb_ld(&(bar)[XB_TMO])) break; if (_sp > XB_SPIN_CAP) { atomicAdd(&(bar)[XB_TMO], 1u); break; } } } } while (0)
; __device__ __forceinline__ void xcd_barrier(unsigned* bar, volatile LAS unsigned* st, bool tid0) {
;     ...
;             const unsigned og = xb_add(&bar[XB_TOP], 1u);
;             const unsigned tg = og / nx;
;             if (og + 1u == (tg + 1u) * nx) xb_add(&bar[XB_TOPGEN], 1u);
;             else XB_SPIN(xb_ld(&bar[XB_TOPGEN]) == tg, bar);
;             __builtin_amdgcn_fence(__ATOMIC_ACQUIRE, "agent");
.LBB0_805:
	s_or_b64 exec, exec, s[16:17]
	buffer_inv sc1
	v_cvt_f32_u32_e32 v3, v0
	s_waitcnt vmcnt(1)
	v_readfirstlane_b32 s2, v2
	s_add_u32 s16, s52, 0x3500
	s_addc_u32 s17, s53, 0
	v_rcp_iflag_f32_e32 v3, v3
	v_add_u32_e32 v1, s2, v1
	v_add_u32_e32 v4, 1, v1
	s_mov_b64 s[18:19], -1
	v_mul_f32_e32 v2, 0x4f7ffffe, v3
	v_cvt_u32_f32_e32 v2, v2
	v_sub_u32_e32 v3, 0, v0
	v_mul_lo_u32 v3, v3, v2
	v_mul_hi_u32 v3, v2, v3
	v_add_u32_e32 v2, v2, v3
	v_mul_hi_u32 v2, v1, v2
	v_mul_lo_u32 v3, v2, v0
	v_sub_u32_e32 v1, v1, v3
	v_add_u32_e32 v5, 1, v2
	v_cmp_ge_u32_e32 vcc, v1, v0
	v_sub_u32_e32 v3, v1, v0
	s_nop 0
	v_cndmask_b32_e32 v2, v2, v5, vcc
	v_cndmask_b32_e32 v1, v1, v3, vcc
	v_add_u32_e32 v3, 1, v2
	v_cmp_ge_u32_e32 vcc, v1, v0
	s_nop 1
	v_cndmask_b32_e32 v2, v2, v3, vcc
	v_mul_lo_u32 v1, v0, v2
	v_add_u32_e32 v0, v1, v0
	v_cmp_ne_u32_e32 vcc, v4, v0
	v_mov_b64_e32 v[0:1], s[16:17]
	s_cbranch_vccnz .Lxb_bcast_skip_8
	v_mov_b32_e32 v3, 0x2400
	v_mov_b32_e32 v4, 1
	global_atomic_add v3, v4, s[52:53]
	global_atomic_add v3, v4, s[52:53] offset:256
	global_atomic_add v3, v4, s[52:53] offset:512
	global_atomic_add v3, v4, s[52:53] offset:768
	global_atomic_add v3, v4, s[52:53] offset:1024
	global_atomic_add v3, v4, s[52:53] offset:1280
	global_atomic_add v3, v4, s[52:53] offset:1536
	global_atomic_add v3, v4, s[52:53] offset:1792
	global_atomic_add v3, v4, s[52:53] offset:2048
	global_atomic_add v3, v4, s[52:53] offset:2304
	global_atomic_add v3, v4, s[52:53] offset:2560
	global_atomic_add v3, v4, s[52:53] offset:2816
	global_atomic_add v3, v4, s[52:53] offset:3072
	global_atomic_add v3, v4, s[52:53] offset:3328
	global_atomic_add v3, v4, s[52:53] offset:3584
	global_atomic_add v3, v4, s[52:53] offset:3840

; __device__ __forceinline__ unsigned xb_ld(unsigned* p)              { return __hip_atomic_load(p, __ATOMIC_RELAXED, __HIP_MEMORY_SCOPE_AGENT); }
; __device__ __forceinline__ unsigned xb_add(unsigned* p, unsigned v) { return __hip_atomic_fetch_add(p, v, __ATOMIC_RELAXED, __HIP_MEMORY_SCOPE_AGENT); }
; #define XB_SPIN(cond, bar) do { unsigned _sp = 0; while (cond) { __builtin_amdgcn_s_sleep(1); \
;     if ((++_sp & 255u) == 0u) { if (xb_ld(&(bar)[XB_TMO])) break; if (_sp > XB_SPIN_CAP) { atomicAdd(&(bar)[XB_TMO], 1u); break; } } } } while (0)
; __device__ __forceinline__ void xcd_barrier(unsigned* bar, volatile LAS unsigned* st, bool tid0) {
;     ...
;             const unsigned og = xb_add(&bar[XB_TOP], 1u);
;             const unsigned tg = og / nx;
;             if (og + 1u == (tg + 1u) * nx) xb_add(&bar[XB_TOPGEN], 1u);
;             else XB_SPIN(xb_ld(&bar[XB_TOPGEN]) == tg, bar);
;             __builtin_amdgcn_fence(__ATOMIC_ACQUIRE, "agent");
.LBB0_1067:
	s_or_b64 exec, exec, s[8:9]
	buffer_inv sc1
	v_cvt_f32_u32_e32 v3, v0
	s_waitcnt vmcnt(1)
	v_readfirstlane_b32 s6, v2
	s_add_u32 s8, s52, 0x3500
	s_addc_u32 s9, s53, 0
	v_rcp_iflag_f32_e32 v3, v3
	v_add_u32_e32 v1, s6, v1
	v_add_u32_e32 v4, 1, v1
	s_mov_b64 s[12:13], -1
	v_mul_f32_e32 v2, 0x4f7ffffe, v3
	v_cvt_u32_f32_e32 v2, v2
	v_sub_u32_e32 v3, 0, v0
	v_mul_lo_u32 v3, v3, v2
	v_mul_hi_u32 v3, v2, v3
	v_add_u32_e32 v2, v2, v3
	v_mul_hi_u32 v2, v1, v2
	v_mul_lo_u32 v3, v2, v0
	v_sub_u32_e32 v1, v1, v3
	v_add_u32_e32 v5, 1, v2
	v_cmp_ge_u32_e32 vcc, v1, v0
	v_sub_u32_e32 v3, v1, v0
	s_nop 0
	v_cndmask_b32_e32 v2, v2, v5, vcc
	v_cndmask_b32_e32 v1, v1, v3, vcc
	v_add_u32_e32 v3, 1, v2
	v_cmp_ge_u32_e32 vcc, v1, v0
	s_nop 1
	v_cndmask_b32_e32 v2, v2, v3, vcc
	v_mul_lo_u32 v1, v0, v2
	v_add_u32_e32 v0, v1, v0
	v_cmp_ne_u32_e32 vcc, v4, v0
	v_mov_b64_e32 v[0:1], s[8:9]
	s_cbranch_vccnz .Lxb_bcast_skip_11
	v_mov_b32_e32 v3, 0x2400
	v_mov_b32_e32 v4, 1
	global_atomic_add v3, v4, s[52:53]
	global_atomic_add v3, v4, s[52:53] offset:256
	global_atomic_add v3, v4, s[52:53] offset:512
	global_atomic_add v3, v4, s[52:53] offset:768
	global_atomic_add v3, v4, s[52:53] offset:1024
	global_atomic_add v3, v4, s[52:53] offset:1280
	global_atomic_add v3, v4, s[52:53] offset:1536
	global_atomic_add v3, v4, s[52:53] offset:1792
	global_atomic_add v3, v4, s[52:53] offset:2048
	global_atomic_add v3, v4, s[52:53] offset:2304
	global_atomic_add v3, v4, s[52:53] offset:2560
	global_atomic_add v3, v4, s[52:53] offset:2816
	global_atomic_add v3, v4, s[52:53] offset:3072
	global_atomic_add v3, v4, s[52:53] offset:3328
	global_atomic_add v3, v4, s[52:53] offset:3584
	global_atomic_add v3, v4, s[52:53] offset:3840
